# speedup vs baseline: 1.0350x; 1.0020x over previous
; template <int MODE>
; __device__ __forceinline__ void attn_unit(LAS unsigned char* lds, const bf16_t* __restrict__ qkvz, bf16_t* __restrict__ A2, const int b, const int hd, const int qb, const AttnX& X, const int tid) {
;     ...
;         if (WIDE) {
; #pragma unroll
;             for (int kk = 0; kk < 2; ++kk) {
;                 if (active) {
;                     f32x16 S;
; #pragma unroll
;                     for (int i = 0; i < 16; ++i) S[i] = 0.f;
;                     const LAS unsigned char* kb = lds + cur * STG + kbase_off + kk * 32 * PK;
;                     __builtin_amdgcn_s_setprio(1);
; #pragma unroll
;                     for (int s = 0; s < NS; ++s) { const bf16x8 a0 = *(const LAS bf16x8*)(kb + s * 32); S = __builtin_amdgcn_mfma_f32_32x32x16_bf16(a0, qf[s], S, 0, 0, 0); }
;                     __builtin_amdgcn_s_setprio(0);
;                     S = S * c2;
;                     float a0 = fmaxf(fmaxf(S[0], S[1]), S[2]), a1 = fmaxf(fmaxf(S[3], S[4]), S[5]);
; #pragma unroll
;                     for (int i = 6; i < 14; i += 4) { a0 = fmaxf(fmaxf(a0, S[i]), S[i + 1]); a1 = fmaxf(fmaxf(a1, S[i + 2]), S[i + 3]); }
;                     const float mx = swap_max(fmaxf(fmaxf(a0, a1), fmaxf(S[14], S[15])));
;                     const float m_new = fmaxf(m_run, mx);
;                     if (__any(mx > m_run + RESCALE_THR)) {
;                         const float alpha = __builtin_amdgcn_exp2f(m_run - m_new);
;                         l_run *= alpha;
; #pragma unroll
;                         for (int d = 0; d < NDT; ++d) O[d] = O[d] * alpha;
;                         m_run = m_new;
;                     }
;                     S = S - m_run;
; #pragma unroll
;                     for (int i = 0; i < 16; ++i) S[i] = __builtin_amdgcn_exp2f(S[i]);
;                     { const f32x4 t4 = (__builtin_shufflevector(S, S, 0, 1, 2, 3) + __builtin_shufflevector(S, S, 4, 5, 6, 7)) + (__builtin_shufflevector(S, S, 8, 9, 10, 11) + __builtin_shufflevector(S, S, 12, 13, 14, 15));
;                       l_run += (t4[0] + t4[1]) + (t4[2] + t4[3]); }
;                     bf16x8 P2[2];
; #pragma unroll
;                     for (int s2 = 0; s2 < 2; ++s2) { u32x4 w0;
;                         w0.x = pk2(S[8 * s2 + 0], S[8 * s2 + 1]); w0.y = pk2(S[8 * s2 + 2], S[8 * s2 + 3]); w0.z = pk2(S[8 * s2 + 4], S[8 * s2 + 5]); w0.w = pk2(S[8 * s2 + 6], S[8 * s2 + 7]);
.LBB0_292:
	s_cmp_lg_u32 s38, 0
	s_cbranch_scc1 .Ldf_nodelay
	s_sleep 11

; __device__ __forceinline__ unsigned pk2(float lo, float hi) { f32x2 v = {lo, hi}; bf16x2_t b = __builtin_convertvector(v, bf16x2_t); return __builtin_bit_cast(unsigned, b); }
; __device__ __forceinline__ float silu_f(float z) { return z * __builtin_amdgcn_rcpf(1.0f + __expf(-z)); }
; __device__ __forceinline__ int launder_v(int x) { asm volatile("" : "+v"(x)); return x; }
; __device__ __forceinline__ int launder_s(int x) { asm volatile("" : "+s"(x)); return x; }
; __device__ __forceinline__ float swap_add(float v) { unsigned a = __builtin_bit_cast(unsigned, v), b = a; asm volatile("s_nop 1\n\tv_permlane32_swap_b32 %0, %1\n\ts_nop 1" : "+v"(a), "+v"(b)); return __builtin_bit_cast(float, a) + __builtin_bit_cast(float, b); }
; template <int MODE>
; __device__ __forceinline__ void attn_unit(LAS unsigned char* lds, const bf16_t* __restrict__ qkvz, bf16_t* __restrict__ A2, const int b, const int hd, const int qb, const AttnX& X, const int tid) {
;     ...
;     const float l_tot = swap_add(l_run);
;     const float inv = 1.0f / l_tot;
;     const int lane_e = launder_v(lane);
;     const size_t trow = (size_t)launder_s(b) * SEQ + launder_s(q0w) + (lane_e & 31);
;     if (MODE != 0) {
;         const int hh_e = lane_e >> 5;
;         u32x2 zz[NDT * 4];
; #pragma unroll
;         for (int d = 0; d < NDT; ++d)
; #pragma unroll
;             for (int i4 = 0; i4 < 4; ++i4) zz[d * 4 + i4] = *(const u32x2*)(qkvz + trow * LD + zcol + 32 * d + 8 * i4 + 4 * hh_e);
; #pragma unroll
;         for (int d = 0; d < NDT; ++d)
; #pragma unroll
;             for (int i4 = 0; i4 < 4; ++i4) { const int dd = 32 * d + 8 * i4 + 4 * hh_e; const u32x2 z2 = zz[d * 4 + i4];
;                 u32x2 w;
;                 w.x = pk2(O[d][4 * i4 + 0] * inv * silu_f(bflo(z2.x)), O[d][4 * i4 + 1] * inv * silu_f(bfhi(z2.x)));
;                 w.y = pk2(O[d][4 * i4 + 2] * inv * silu_f(bflo(z2.y)), O[d][4 * i4 + 3] * inv * silu_f(bfhi(z2.y)));
;                 *(u32x2*)(A2 + trow * DM + hd * C::DV + dd) = w; }
; __device__ __forceinline__ void phase_attn_band(const Params& p, LAS unsigned char* lds) {
;     ...
;     for (int u = bx; u < 4096; u += G) attn_unit<1>(lds, QKVZ, A2, u >> 10, (u >> 5) & 31, u & 31, X, tid);
.LBB0_585:
	s_nop 1
	v_mov_b32_e32 v40, v146
	v_mov_b32_e32 v36, v125
	s_nop 1
	v_permlane32_swap_b32 v146, v40
	s_nop 1
	s_ashr_i32 s29, s28, 31
	s_lshl_b64 s[0:1], s[28:29], 13
	s_ashr_i32 s12, s39, 31
	s_add_u32 s0, s0, s39
	v_and_b32_e32 v80, 31, v36
	s_addc_u32 s1, s1, s12
	v_lshl_add_u64 v[32:33], s[0:1], 0, v[80:81]
	v_ashrrev_i32_e32 v36, 3, v36
	v_lshlrev_b64 v[34:35], 14, v[32:33]
	v_and_b32_e32 v36, -4, v36
	v_lshl_add_u64 v[34:35], s[84:85], 0, v[34:35]
	v_ashrrev_i32_e32 v37, 31, v36
	v_lshl_add_u64 v[34:35], v[34:35], 0, s[14:15]
	v_lshlrev_b64 v[36:37], 1, v[36:37]
	v_lshl_add_u64 v[34:35], v[34:35], 0, v[36:37]
	v_add_co_u32_e32 v38, vcc, s33, v34
	v_add_f32_e32 v52, v146, v40
	s_nop 0
	v_addc_co_u32_e32 v39, vcc, 0, v35, vcc
	global_load_dwordx2 v[42:43], v[38:39], off
	v_lshl_add_u64 v[34:35], v[34:35], 0, s[26:27]
	global_load_dwordx2 v[44:45], v[34:35], off offset:16
	global_load_dwordx2 v[46:47], v[34:35], off offset:32
	v_div_scale_f32 v53, s[0:1], v52, v52, 1.0
	v_rcp_f32_e32 v54, v53
	v_lshlrev_b64 v[32:33], 12, v[32:33]
	v_lshl_add_u64 v[32:33], s[94:95], 0, v[32:33]
	v_lshl_add_u64 v[32:33], v[32:33], 0, s[14:15]
	v_fma_f32 v38, -v53, v54, 1.0
	v_fmac_f32_e32 v54, v38, v54
	v_lshl_add_u64 v[32:33], v[32:33], 0, v[36:37]
	global_load_dwordx2 v[48:49], v[34:35], off offset:48
	global_load_dwordx2 v[50:51], v[34:35], off offset:64
	global_load_dwordx2 v[40:41], v[34:35], off offset:80
	global_load_dwordx2 v[38:39], v[34:35], off offset:96
	global_load_dwordx2 v[36:37], v[34:35], off offset:112
	v_div_scale_f32 v55, vcc, 1.0, v52, 1.0
	v_mul_f32_e32 v56, v55, v54
	v_fma_f32 v57, -v53, v56, v55
	v_fmac_f32_e32 v56, v57, v54
	v_fma_f32 v34, -v53, v56, v55
	v_div_fmas_f32 v34, v34, v54, v56
	v_div_fixup_f32 v34, v34, v52, 1.0
	v_pk_mul_f32 v[16:17], v[16:17], v[34:35] op_sel_hi:[1,0]
	v_pk_mul_f32 v[18:19], v[18:19], v[34:35] op_sel_hi:[1,0]
	v_pk_mul_f32 v[20:21], v[20:21], v[34:35] op_sel_hi:[1,0]
	v_pk_mul_f32 v[22:23], v[22:23], v[34:35] op_sel_hi:[1,0]
	s_waitcnt vmcnt(7)
	v_lshlrev_b32_e32 v52, 16, v42
	v_and_b32_e32 v53, 0xffff0000, v42
	v_lshlrev_b32_e32 v42, 16, v43
	v_and_b32_e32 v43, 0xffff0000, v43
	s_waitcnt vmcnt(6)
	v_lshlrev_b32_e32 v54, 16, v44
	v_mul_f32_e32 v35, 0xbfb8aa3b, v52
	v_mul_f32_e32 v56, 0xbfb8aa3b, v53
	v_mul_f32_e32 v57, 0xbfb8aa3b, v42
	v_mul_f32_e32 v58, 0xbfb8aa3b, v43
	v_mul_f32_e32 v59, 0xbfb8aa3b, v54
	v_exp_f32_e32 v35, v35
	v_exp_f32_e32 v56, v56
	v_exp_f32_e32 v57, v57
	v_exp_f32_e32 v58, v58
	v_and_b32_e32 v55, 0xffff0000, v44
	v_lshlrev_b32_e32 v44, 16, v45
	v_and_b32_e32 v45, 0xffff0000, v45
	v_exp_f32_e32 v59, v59
	v_mul_f32_e32 v61, 0xbfb8aa3b, v44
	v_mul_f32_e32 v62, 0xbfb8aa3b, v45
	v_mul_f32_e32 v60, 0xbfb8aa3b, v55
	v_exp_f32_e32 v61, v61
	v_exp_f32_e32 v62, v62
	v_exp_f32_e32 v60, v60
	v_add_f32_e32 v35, 1.0, v35
	v_add_f32_e32 v63, 1.0, v56
	v_add_f32_e32 v64, 1.0, v57
	v_add_f32_e32 v65, 1.0, v58
	v_add_f32_e32 v66, 1.0, v59
	v_rcp_f32_e32 v56, v35
	v_rcp_f32_e32 v57, v63
	v_rcp_f32_e32 v58, v64
	v_rcp_f32_e32 v59, v65
	v_add_f32_e32 v68, 1.0, v61
	v_add_f32_e32 v69, 1.0, v62
	v_add_f32_e32 v67, 1.0, v60
	v_rcp_f32_e32 v62, v68
	v_rcp_f32_e32 v63, v69
	v_rcp_f32_e32 v60, v66
	v_rcp_f32_e32 v61, v67
	v_pk_mul_f32 v[52:53], v[56:57], v[52:53]
	v_pk_mul_f32 v[42:43], v[58:59], v[42:43]
	v_pk_mul_f32 v[16:17], v[16:17], v[52:53]
	v_pk_mul_f32 v[18:19], v[18:19], v[42:43]
	v_cvt_pk_bf16_f32 v16, v16, v17
	v_cvt_pk_bf16_f32 v17, v18, v19
	global_store_dwordx2 v[32:33], v[16:17], off
	v_pk_mul_f32 v[16:17], v[62:63], v[44:45]
	v_pk_mul_f32 v[54:55], v[60:61], v[54:55]
	v_pk_mul_f32 v[16:17], v[22:23], v[16:17]
	v_pk_mul_f32 v[20:21], v[20:21], v[54:55]
	v_cvt_pk_bf16_f32 v19, v16, v17
	s_waitcnt vmcnt(6)
	v_lshlrev_b32_e32 v16, 16, v46
	v_cvt_pk_bf16_f32 v18, v20, v21
	v_mul_f32_e32 v17, 0xbfb8aa3b, v16
	global_store_dwordx2 v[32:33], v[18:19], off offset:16
	v_exp_f32_e32 v18, v17
	v_and_b32_e32 v17, 0xffff0000, v46
	v_mul_f32_e32 v19, 0xbfb8aa3b, v17
	v_exp_f32_e32 v19, v19
	v_lshlrev_b32_e32 v22, 16, v47
	v_and_b32_e32 v23, 0xffff0000, v47
	v_add_f32_e32 v18, 1.0, v18
	v_pk_mul_f32 v[20:21], v[24:25], v[34:35] op_sel_hi:[1,0]
	v_add_f32_e32 v19, 1.0, v19
	v_mul_f32_e32 v24, 0xbfb8aa3b, v22
	v_mul_f32_e32 v25, 0xbfb8aa3b, v23
	v_rcp_f32_e32 v18, v18
	v_rcp_f32_e32 v19, v19
	v_exp_f32_e32 v24, v24
	v_exp_f32_e32 v25, v25
	v_pk_mul_f32 v[0:1], v[0:1], v[34:35] op_sel_hi:[1,0]
	v_pk_mul_f32 v[16:17], v[18:19], v[16:17]
	v_add_f32_e32 v18, 1.0, v24
	v_add_f32_e32 v19, 1.0, v25
	v_rcp_f32_e32 v18, v18
	v_rcp_f32_e32 v19, v19
	v_pk_mul_f32 v[16:17], v[20:21], v[16:17]
	v_pk_mul_f32 v[20:21], v[26:27], v[34:35] op_sel_hi:[1,0]
	v_cvt_pk_bf16_f32 v16, v16, v17
	v_pk_mul_f32 v[18:19], v[18:19], v[22:23]
	s_waitcnt vmcnt(6)
; __device__ __forceinline__ unsigned pk2(float lo, float hi) { f32x2 v = {lo, hi}; bf16x2_t b = __builtin_convertvector(v, bf16x2_t); return __builtin_bit_cast(unsigned, b); }
; __device__ __forceinline__ float silu_f(float z) { return z * __builtin_amdgcn_rcpf(1.0f + __expf(-z)); }
; template <int MODE>
; __device__ __forceinline__ void attn_unit(LAS unsigned char* lds, const bf16_t* __restrict__ qkvz, bf16_t* __restrict__ A2, const int b, const int hd, const int qb, const AttnX& X, const int tid) {
;     ...
; #pragma unroll
;         for (int d = 0; d < NDT; ++d)
; #pragma unroll
;             for (int i4 = 0; i4 < 4; ++i4) { const int dd = 32 * d + 8 * i4 + 4 * hh_e; const u32x2 z2 = zz[d * 4 + i4];
;                 u32x2 w;
;                 w.x = pk2(O[d][4 * i4 + 0] * inv * silu_f(bflo(z2.x)), O[d][4 * i4 + 1] * inv * silu_f(bfhi(z2.x)));
;                 w.y = pk2(O[d][4 * i4 + 2] * inv * silu_f(bflo(z2.y)), O[d][4 * i4 + 3] * inv * silu_f(bfhi(z2.y)));
;                 *(u32x2*)(A2 + trow * DM + hd * C::DV + dd) = w; }
; __device__ __forceinline__ void phase_attn_band(const Params& p, LAS unsigned char* lds) {
;     ...
;     for (int u = bx; u < 4096; u += G) attn_unit<1>(lds, QKVZ, A2, u >> 10, (u >> 5) & 31, u & 31, X, tid);
	v_lshlrev_b32_e32 v22, 16, v49
	v_pk_mul_f32 v[18:19], v[20:21], v[18:19]
	v_and_b32_e32 v23, 0xffff0000, v49
	v_cvt_pk_bf16_f32 v17, v18, v19
	global_store_dwordx2 v[32:33], v[16:17], off offset:32
	v_lshlrev_b32_e32 v16, 16, v48
	v_mul_f32_e32 v17, 0xbfb8aa3b, v16
	v_exp_f32_e32 v18, v17
	v_and_b32_e32 v17, 0xffff0000, v48
	v_mul_f32_e32 v19, 0xbfb8aa3b, v17
	v_exp_f32_e32 v19, v19
	v_add_f32_e32 v18, 1.0, v18
	v_mul_f32_e32 v24, 0xbfb8aa3b, v22
	v_mul_f32_e32 v25, 0xbfb8aa3b, v23
	v_add_f32_e32 v19, 1.0, v19
	v_rcp_f32_e32 v18, v18
	v_rcp_f32_e32 v19, v19
	v_exp_f32_e32 v24, v24
	v_exp_f32_e32 v25, v25
	v_pk_mul_f32 v[20:21], v[28:29], v[34:35] op_sel_hi:[1,0]
	v_pk_mul_f32 v[16:17], v[18:19], v[16:17]
	v_add_f32_e32 v18, 1.0, v24
	v_add_f32_e32 v19, 1.0, v25
	v_rcp_f32_e32 v18, v18
	v_rcp_f32_e32 v19, v19
	v_pk_mul_f32 v[16:17], v[20:21], v[16:17]
	v_pk_mul_f32 v[20:21], v[30:31], v[34:35] op_sel_hi:[1,0]
	v_cvt_pk_bf16_f32 v16, v16, v17
	v_pk_mul_f32 v[18:19], v[18:19], v[22:23]
	v_pk_mul_f32 v[2:3], v[2:3], v[34:35] op_sel_hi:[1,0]
	v_pk_mul_f32 v[18:19], v[20:21], v[18:19]
	s_waitcnt vmcnt(6)
	v_lshlrev_b32_e32 v20, 16, v51
	v_cvt_pk_bf16_f32 v17, v18, v19
	global_store_dwordx2 v[32:33], v[16:17], off offset:48
	v_lshlrev_b32_e32 v16, 16, v50
	v_mul_f32_e32 v17, 0xbfb8aa3b, v16
	v_exp_f32_e32 v18, v17
	v_and_b32_e32 v17, 0xffff0000, v50
	v_mul_f32_e32 v19, 0xbfb8aa3b, v17
	v_exp_f32_e32 v19, v19
	v_and_b32_e32 v21, 0xffff0000, v51
	v_add_f32_e32 v18, 1.0, v18
	v_mul_f32_e32 v22, 0xbfb8aa3b, v20
	v_add_f32_e32 v19, 1.0, v19
	v_mul_f32_e32 v23, 0xbfb8aa3b, v21
	v_rcp_f32_e32 v18, v18
	v_rcp_f32_e32 v19, v19
	v_exp_f32_e32 v22, v22
	v_exp_f32_e32 v23, v23
	v_pk_mul_f32 v[4:5], v[4:5], v[34:35] op_sel_hi:[1,0]
	v_pk_mul_f32 v[16:17], v[18:19], v[16:17]
	v_add_f32_e32 v18, 1.0, v22
	v_add_f32_e32 v19, 1.0, v23
	v_rcp_f32_e32 v18, v18
	v_rcp_f32_e32 v19, v19
	v_pk_mul_f32 v[0:1], v[0:1], v[16:17]
	v_pk_mul_f32 v[16:17], v[18:19], v[20:21]
	s_nop 0
	v_pk_mul_f32 v[2:3], v[2:3], v[16:17]
	v_cvt_pk_bf16_f32 v0, v0, v1
	v_cvt_pk_bf16_f32 v1, v2, v3
	global_store_dwordx2 v[32:33], v[0:1], off offset:64
	s_waitcnt vmcnt(7)
	v_lshlrev_b32_e32 v0, 16, v40
	v_mul_f32_e32 v1, 0xbfb8aa3b, v0
	v_exp_f32_e32 v2, v1
	v_and_b32_e32 v1, 0xffff0000, v40
	v_mul_f32_e32 v3, 0xbfb8aa3b, v1
	v_exp_f32_e32 v3, v3
	v_lshlrev_b32_e32 v16, 16, v41
	v_and_b32_e32 v17, 0xffff0000, v41
	v_add_f32_e32 v2, 1.0, v2
	v_add_f32_e32 v3, 1.0, v3
	v_mul_f32_e32 v18, 0xbfb8aa3b, v16
	v_mul_f32_e32 v19, 0xbfb8aa3b, v17
	v_rcp_f32_e32 v2, v2
	v_rcp_f32_e32 v3, v3
	v_exp_f32_e32 v18, v18
	v_exp_f32_e32 v19, v19
	v_pk_mul_f32 v[0:1], v[2:3], v[0:1]
	v_add_f32_e32 v2, 1.0, v18
	v_add_f32_e32 v3, 1.0, v19
	v_rcp_f32_e32 v2, v2
	v_rcp_f32_e32 v3, v3
	v_pk_mul_f32 v[0:1], v[4:5], v[0:1]
	v_pk_mul_f32 v[4:5], v[6:7], v[34:35] op_sel_hi:[1,0]
	v_cvt_pk_bf16_f32 v0, v0, v1
	v_pk_mul_f32 v[2:3], v[2:3], v[16:17]
	s_waitcnt vmcnt(6)
	v_lshlrev_b32_e32 v6, 16, v39
	v_pk_mul_f32 v[2:3], v[4:5], v[2:3]
	v_and_b32_e32 v7, 0xffff0000, v39
	v_cvt_pk_bf16_f32 v1, v2, v3
	global_store_dwordx2 v[32:33], v[0:1], off offset:80
	v_lshlrev_b32_e32 v0, 16, v38
	v_mul_f32_e32 v1, 0xbfb8aa3b, v0
	v_exp_f32_e32 v2, v1
	v_and_b32_e32 v1, 0xffff0000, v38
	v_mul_f32_e32 v3, 0xbfb8aa3b, v1
	v_exp_f32_e32 v3, v3
	v_add_f32_e32 v2, 1.0, v2
	v_pk_mul_f32 v[4:5], v[8:9], v[34:35] op_sel_hi:[1,0]
	v_mul_f32_e32 v8, 0xbfb8aa3b, v6
	v_add_f32_e32 v3, 1.0, v3
	v_mul_f32_e32 v9, 0xbfb8aa3b, v7
	v_rcp_f32_e32 v2, v2
	v_rcp_f32_e32 v3, v3
	v_exp_f32_e32 v8, v8
	v_exp_f32_e32 v9, v9
	v_pk_mul_f32 v[0:1], v[2:3], v[0:1]
	v_add_f32_e32 v2, 1.0, v8
	v_add_f32_e32 v3, 1.0, v9
	v_rcp_f32_e32 v2, v2
	v_rcp_f32_e32 v3, v3
	v_pk_mul_f32 v[0:1], v[4:5], v[0:1]
	v_pk_mul_f32 v[4:5], v[10:11], v[34:35] op_sel_hi:[1,0]
	v_cvt_pk_bf16_f32 v0, v0, v1
	v_pk_mul_f32 v[2:3], v[2:3], v[6:7]
	s_waitcnt vmcnt(6)
	v_lshlrev_b32_e32 v6, 16, v37
	v_pk_mul_f32 v[2:3], v[4:5], v[2:3]
	v_and_b32_e32 v7, 0xffff0000, v37
	v_cvt_pk_bf16_f32 v1, v2, v3
	global_store_dwordx2 v[32:33], v[0:1], off offset:96
	v_lshlrev_b32_e32 v0, 16, v36
	v_mul_f32_e32 v1, 0xbfb8aa3b, v0
	v_exp_f32_e32 v2, v1
	v_and_b32_e32 v1, 0xffff0000, v36
	v_mul_f32_e32 v3, 0xbfb8aa3b, v1
	v_exp_f32_e32 v3, v3
	v_add_f32_e32 v2, 1.0, v2
	v_mul_f32_e32 v8, 0xbfb8aa3b, v6
	v_mul_f32_e32 v9, 0xbfb8aa3b, v7
	v_add_f32_e32 v3, 1.0, v3
	v_rcp_f32_e32 v2, v2
	v_rcp_f32_e32 v3, v3
	v_exp_f32_e32 v8, v8
	v_exp_f32_e32 v9, v9
	v_pk_mul_f32 v[4:5], v[12:13], v[34:35] op_sel_hi:[1,0]
	v_pk_mul_f32 v[0:1], v[2:3], v[0:1]
	v_add_f32_e32 v2, 1.0, v8
	v_add_f32_e32 v3, 1.0, v9
	v_rcp_f32_e32 v2, v2
	v_rcp_f32_e32 v3, v3
	v_pk_mul_f32 v[0:1], v[4:5], v[0:1]
	v_pk_mul_f32 v[4:5], v[14:15], v[34:35] op_sel_hi:[1,0]
	v_cvt_pk_bf16_f32 v0, v0, v1
	v_pk_mul_f32 v[2:3], v[2:3], v[6:7]
	s_nop 0
	v_pk_mul_f32 v[2:3], v[4:5], v[2:3]
	s_nop 0
	v_cvt_pk_bf16_f32 v1, v2, v3
	global_store_dwordx2 v[32:33], v[0:1], off offset:112
	s_barrier
	v_cmp_eq_u32_e32 vcc, 0, v212
	s_and_saveexec_b64 s[12:13], vcc
	s_cbranch_execz .Lband_nofetch
	v_mov_b32_e32 v0, 0x93a0040
	v_mov_b32_e32 v1, 1
	global_atomic_add v0, v0, v1, s[72:73] sc0
	s_waitcnt vmcnt(0)
	v_mov_b32_e32 v1, 0x23ff8
	ds_write_b32 v1, v0
.Lband_nofetch:
	s_or_b64 exec, exec, s[12:13]
	s_waitcnt lgkmcnt(0)
	s_barrier
	v_mov_b32_e32 v1, 0x23ff8
	ds_read_b32 v0, v1
	s_waitcnt lgkmcnt(0)
	v_readfirstlane_b32 s38, v0
	s_nop 1
	s_add_i32 s38, s38, s17
	s_mov_b32 s25, s38
	s_cmpk_lt_i32 s38, 0x1000
	s_cbranch_scc0 .LBB0_621

; __device__ __forceinline__ unsigned pk2(float lo, float hi) { f32x2 v = {lo, hi}; bf16x2_t b = __builtin_convertvector(v, bf16x2_t); return __builtin_bit_cast(unsigned, b); }
; __device__ __forceinline__ float silu_f(float z) { return z * __builtin_amdgcn_rcpf(1.0f + __expf(-z)); }
; __device__ __forceinline__ int launder_v(int x) { asm volatile("" : "+v"(x)); return x; }
; __device__ __forceinline__ int launder_s(int x) { asm volatile("" : "+s"(x)); return x; }
; __device__ __forceinline__ float swap_add(float v) { unsigned a = __builtin_bit_cast(unsigned, v), b = a; asm volatile("s_nop 1\n\tv_permlane32_swap_b32 %0, %1\n\ts_nop 1" : "+v"(a), "+v"(b)); return __builtin_bit_cast(float, a) + __builtin_bit_cast(float, b); }
; template <int MODE>
; __device__ __forceinline__ void attn_unit(LAS unsigned char* lds, const bf16_t* __restrict__ qkvz, bf16_t* __restrict__ A2, const int b, const int hd, const int qb, const AttnX& X, const int tid) {
;     ...
;     const float l_tot = swap_add(l_run);
;     const float inv = 1.0f / l_tot;
;     const int lane_e = launder_v(lane);
;     const size_t trow = (size_t)launder_s(b) * SEQ + launder_s(q0w) + (lane_e & 31);
;     if (MODE != 0) {
;         const int hh_e = lane_e >> 5;
;         u32x2 zz[NDT * 4];
; #pragma unroll
;         for (int d = 0; d < NDT; ++d)
; #pragma unroll
;             for (int i4 = 0; i4 < 4; ++i4) zz[d * 4 + i4] = *(const u32x2*)(qkvz + trow * LD + zcol + 32 * d + 8 * i4 + 4 * hh_e);
; #pragma unroll
;         for (int d = 0; d < NDT; ++d)
; #pragma unroll
;             for (int i4 = 0; i4 < 4; ++i4) { const int dd = 32 * d + 8 * i4 + 4 * hh_e; const u32x2 z2 = zz[d * 4 + i4];
;                 u32x2 w;
;                 w.x = pk2(O[d][4 * i4 + 0] * inv * silu_f(bflo(z2.x)), O[d][4 * i4 + 1] * inv * silu_f(bfhi(z2.x)));
;                 w.y = pk2(O[d][4 * i4 + 2] * inv * silu_f(bflo(z2.y)), O[d][4 * i4 + 3] * inv * silu_f(bfhi(z2.y)));
;                 *(u32x2*)(A2 + trow * DM + hd * C::DV + dd) = w; }
.LBB0_1003:
	s_or_b64 exec, exec, s[92:93]
	v_mov_b32_e32 v74, v190
	v_mov_b32_e32 v70, v161
	s_nop 1
	v_permlane32_swap_b32 v190, v74
	s_nop 1
	s_ashr_i32 s15, s14, 31
	s_lshl_b64 s[0:1], s[14:15], 13
	s_ashr_i32 s2, s13, 31
	s_add_u32 s0, s0, s13
	v_and_b32_e32 v0, 31, v70
	s_addc_u32 s1, s1, s2
	v_lshl_add_u64 v[66:67], s[0:1], 0, v[0:1]
	v_readlane_b32 s84, v255, 7
	v_ashrrev_i32_e32 v0, 3, v70
	v_lshlrev_b64 v[68:69], 14, v[66:67]
	v_readlane_b32 s85, v255, 8
	v_and_b32_e32 v70, -4, v0
	s_mov_b32 s13, s89
	v_lshl_add_u64 v[68:69], s[84:85], 0, v[68:69]
	v_ashrrev_i32_e32 v71, 31, v70
	v_lshl_add_u64 v[68:69], v[68:69], 0, s[12:13]
	v_lshlrev_b64 v[70:71], 1, v[70:71]
	v_lshl_add_u64 v[68:69], v[68:69], 0, v[70:71]
	s_movk_i32 s0, 0x3000
	v_add_co_u32_e32 v72, vcc, s0, v68
	s_mov_b64 s[0:1], 0x3000
	s_nop 0
	v_addc_co_u32_e32 v73, vcc, 0, v69, vcc
	global_load_dwordx2 v[90:91], v[72:73], off
	v_lshl_add_u64 v[68:69], v[68:69], 0, s[0:1]
	global_load_dwordx2 v[92:93], v[68:69], off offset:16
	global_load_dwordx2 v[94:95], v[68:69], off offset:32
	v_add_f32_e32 v0, v190, v74
	v_div_scale_f32 v100, s[0:1], v0, v0, 1.0
	v_rcp_f32_e32 v101, v100
	v_readlane_b32 s94, v255, 5
	v_lshlrev_b64 v[66:67], 12, v[66:67]
	v_readlane_b32 s95, v255, 6
	v_fma_f32 v72, -v100, v101, 1.0
	v_fmac_f32_e32 v101, v72, v101
	v_lshl_add_u64 v[66:67], s[94:95], 0, v[66:67]
	v_lshl_add_u64 v[66:67], v[66:67], 0, s[12:13]
	v_lshl_add_u64 v[66:67], v[66:67], 0, v[70:71]
	global_load_dwordx2 v[96:97], v[68:69], off offset:48
	global_load_dwordx2 v[98:99], v[68:69], off offset:64
	global_load_dwordx2 v[88:89], v[68:69], off offset:80
	global_load_dwordx2 v[86:87], v[68:69], off offset:96
	global_load_dwordx2 v[84:85], v[68:69], off offset:112
	global_load_dwordx2 v[82:83], v[68:69], off offset:128
	global_load_dwordx2 v[80:81], v[68:69], off offset:144
	global_load_dwordx2 v[78:79], v[68:69], off offset:160
	global_load_dwordx2 v[76:77], v[68:69], off offset:176
	global_load_dwordx2 v[74:75], v[68:69], off offset:192
	global_load_dwordx2 v[72:73], v[68:69], off offset:208
	global_load_dwordx2 v[70:71], v[68:69], off offset:224
	s_nop 0
	global_load_dwordx2 v[68:69], v[68:69], off offset:240
	v_div_scale_f32 v102, vcc, 1.0, v0, 1.0
	v_mul_f32_e32 v103, v102, v101
	v_fma_f32 v104, -v100, v103, v102
	v_fmac_f32_e32 v103, v104, v101
	v_fma_f32 v100, -v100, v103, v102
	v_div_fmas_f32 v100, v100, v101, v103
	v_div_fixup_f32 v0, v100, v0, 1.0
	v_pk_mul_f32 v[50:51], v[50:51], v[0:1] op_sel_hi:[1,0]
	v_pk_mul_f32 v[52:53], v[52:53], v[0:1] op_sel_hi:[1,0]
	v_pk_mul_f32 v[54:55], v[54:55], v[0:1] op_sel_hi:[1,0]
	v_pk_mul_f32 v[34:35], v[34:35], v[0:1] op_sel_hi:[1,0]
	v_pk_mul_f32 v[36:37], v[36:37], v[0:1] op_sel_hi:[1,0]
	v_pk_mul_f32 v[38:39], v[38:39], v[0:1] op_sel_hi:[1,0]
	v_pk_mul_f32 v[18:19], v[18:19], v[0:1] op_sel_hi:[1,0]
	v_pk_mul_f32 v[20:21], v[20:21], v[0:1] op_sel_hi:[1,0]
	v_pk_mul_f32 v[22:23], v[22:23], v[0:1] op_sel_hi:[1,0]
	v_pk_mul_f32 v[2:3], v[2:3], v[0:1] op_sel_hi:[1,0]
	v_pk_mul_f32 v[4:5], v[4:5], v[0:1] op_sel_hi:[1,0]
	v_pk_mul_f32 v[6:7], v[6:7], v[0:1] op_sel_hi:[1,0]
	v_readlane_b32 s0, v254, 47
	v_readlane_b32 s28, v255, 9
	v_readlane_b32 s92, v255, 4
	v_readlane_b32 s29, v255, 10
	s_waitcnt vmcnt(15)
	v_lshlrev_b32_e32 v100, 16, v90
	v_and_b32_e32 v101, 0xffff0000, v90
	v_lshlrev_b32_e32 v90, 16, v91
	v_and_b32_e32 v91, 0xffff0000, v91
	v_mul_f32_e32 v104, 0xbfb8aa3b, v100
	v_mul_f32_e32 v105, 0xbfb8aa3b, v101
	v_mul_f32_e32 v106, 0xbfb8aa3b, v90
	v_mul_f32_e32 v107, 0xbfb8aa3b, v91
	v_exp_f32_e32 v104, v104
	v_exp_f32_e32 v105, v105
	v_exp_f32_e32 v106, v106
	v_exp_f32_e32 v107, v107
	v_add_f32_e32 v104, 1.0, v104
	v_add_f32_e32 v105, 1.0, v105
	v_add_f32_e32 v106, 1.0, v106
	v_add_f32_e32 v107, 1.0, v107
	v_rcp_f32_e32 v104, v104
	v_rcp_f32_e32 v105, v105
	v_rcp_f32_e32 v106, v106
	v_rcp_f32_e32 v107, v107
	s_waitcnt vmcnt(14)
	v_lshlrev_b32_e32 v102, 16, v92
	v_and_b32_e32 v103, 0xffff0000, v92
	v_lshlrev_b32_e32 v92, 16, v93
	v_and_b32_e32 v93, 0xffff0000, v93
	v_mul_f32_e32 v108, 0xbfb8aa3b, v102
	v_mul_f32_e32 v109, 0xbfb8aa3b, v103
	v_pk_mul_f32 v[100:101], v[104:105], v[100:101]
	v_pk_mul_f32 v[90:91], v[106:107], v[90:91]
	v_mul_f32_e32 v110, 0xbfb8aa3b, v92
	v_mul_f32_e32 v111, 0xbfb8aa3b, v93
	v_exp_f32_e32 v108, v108
	v_exp_f32_e32 v109, v109
	v_pk_mul_f32 v[50:51], v[50:51], v[100:101]
	v_pk_mul_f32 v[52:53], v[52:53], v[90:91]
	v_exp_f32_e32 v110, v110
	v_cvt_pk_bf16_f32 v50, v50, v51
	v_cvt_pk_bf16_f32 v51, v52, v53
	v_exp_f32_e32 v53, v111
	v_add_f32_e32 v108, 1.0, v108
	v_add_f32_e32 v109, 1.0, v109
	v_rcp_f32_e32 v108, v108
	v_rcp_f32_e32 v109, v109
	v_add_f32_e32 v52, 1.0, v110
	v_add_f32_e32 v53, 1.0, v53
	v_rcp_f32_e32 v52, v52
	v_rcp_f32_e32 v53, v53
	global_store_dwordx2 v[66:67], v[50:51], off
	v_pk_mul_f32 v[50:51], v[108:109], v[102:103]
	v_pk_mul_f32 v[52:53], v[52:53], v[92:93]
	v_pk_mul_f32 v[50:51], v[54:55], v[50:51]
	v_pk_mul_f32 v[54:55], v[56:57], v[0:1] op_sel_hi:[1,0]
	v_cvt_pk_bf16_f32 v50, v50, v51
	v_pk_mul_f32 v[52:53], v[54:55], v[52:53]
	s_waitcnt vmcnt(14)
	v_lshlrev_b32_e32 v56, 16, v95
	v_cvt_pk_bf16_f32 v51, v52, v53
	global_store_dwordx2 v[66:67], v[50:51], off offset:16
	v_lshlrev_b32_e32 v50, 16, v94
	v_mul_f32_e32 v51, 0xbfb8aa3b, v50
	v_exp_f32_e32 v52, v51
	v_and_b32_e32 v51, 0xffff0000, v94
	v_mul_f32_e32 v53, 0xbfb8aa3b, v51
	v_exp_f32_e32 v53, v53
	v_and_b32_e32 v57, 0xffff0000, v95
	v_add_f32_e32 v52, 1.0, v52
	v_pk_mul_f32 v[54:55], v[58:59], v[0:1] op_sel_hi:[1,0]
	v_add_f32_e32 v53, 1.0, v53
	v_mul_f32_e32 v58, 0xbfb8aa3b, v56
	v_mul_f32_e32 v59, 0xbfb8aa3b, v57
	v_rcp_f32_e32 v52, v52
	v_rcp_f32_e32 v53, v53
	v_exp_f32_e32 v58, v58
	v_exp_f32_e32 v59, v59
	v_pk_mul_f32 v[50:51], v[52:53], v[50:51]
	v_add_f32_e32 v52, 1.0, v58
	v_add_f32_e32 v53, 1.0, v59
	v_rcp_f32_e32 v52, v52
	v_rcp_f32_e32 v53, v53
	v_pk_mul_f32 v[50:51], v[54:55], v[50:51]
	v_pk_mul_f32 v[54:55], v[60:61], v[0:1] op_sel_hi:[1,0]
	v_cvt_pk_bf16_f32 v50, v50, v51
	v_pk_mul_f32 v[52:53], v[52:53], v[56:57]
	s_waitcnt vmcnt(14)
; __device__ __forceinline__ unsigned pk2(float lo, float hi) { f32x2 v = {lo, hi}; bf16x2_t b = __builtin_convertvector(v, bf16x2_t); return __builtin_bit_cast(unsigned, b); }
; __device__ __forceinline__ float silu_f(float z) { return z * __builtin_amdgcn_rcpf(1.0f + __expf(-z)); }
; template <int MODE>
; __device__ __forceinline__ void attn_unit(LAS unsigned char* lds, const bf16_t* __restrict__ qkvz, bf16_t* __restrict__ A2, const int b, const int hd, const int qb, const AttnX& X, const int tid) {
;     ...
; #pragma unroll
;         for (int d = 0; d < NDT; ++d)
; #pragma unroll
;             for (int i4 = 0; i4 < 4; ++i4) { const int dd = 32 * d + 8 * i4 + 4 * hh_e; const u32x2 z2 = zz[d * 4 + i4];
;                 u32x2 w;
;                 w.x = pk2(O[d][4 * i4 + 0] * inv * silu_f(bflo(z2.x)), O[d][4 * i4 + 1] * inv * silu_f(bfhi(z2.x)));
;                 w.y = pk2(O[d][4 * i4 + 2] * inv * silu_f(bflo(z2.y)), O[d][4 * i4 + 3] * inv * silu_f(bfhi(z2.y)));
;                 *(u32x2*)(A2 + trow * DM + hd * C::DV + dd) = w; }
	v_lshlrev_b32_e32 v56, 16, v97
	v_pk_mul_f32 v[52:53], v[54:55], v[52:53]
	v_and_b32_e32 v57, 0xffff0000, v97
	v_cvt_pk_bf16_f32 v51, v52, v53
	global_store_dwordx2 v[66:67], v[50:51], off offset:32
	v_lshlrev_b32_e32 v50, 16, v96
	v_mul_f32_e32 v51, 0xbfb8aa3b, v50
	v_exp_f32_e32 v52, v51
	v_and_b32_e32 v51, 0xffff0000, v96
	v_mul_f32_e32 v53, 0xbfb8aa3b, v51
	v_exp_f32_e32 v53, v53
	v_add_f32_e32 v52, 1.0, v52
	v_mul_f32_e32 v58, 0xbfb8aa3b, v56
	v_mul_f32_e32 v59, 0xbfb8aa3b, v57
	v_add_f32_e32 v53, 1.0, v53
	v_rcp_f32_e32 v52, v52
	v_rcp_f32_e32 v53, v53
	v_exp_f32_e32 v58, v58
	v_exp_f32_e32 v59, v59
	v_pk_mul_f32 v[54:55], v[62:63], v[0:1] op_sel_hi:[1,0]
	v_pk_mul_f32 v[50:51], v[52:53], v[50:51]
	v_add_f32_e32 v52, 1.0, v58
	v_add_f32_e32 v53, 1.0, v59
	v_rcp_f32_e32 v52, v52
	v_rcp_f32_e32 v53, v53
	v_pk_mul_f32 v[50:51], v[54:55], v[50:51]
	v_pk_mul_f32 v[54:55], v[64:65], v[0:1] op_sel_hi:[1,0]
	v_cvt_pk_bf16_f32 v50, v50, v51
	v_pk_mul_f32 v[52:53], v[52:53], v[56:57]
	s_nop 0
	v_pk_mul_f32 v[52:53], v[54:55], v[52:53]
	s_waitcnt vmcnt(14)
	v_lshlrev_b32_e32 v54, 16, v99
	v_cvt_pk_bf16_f32 v51, v52, v53
	global_store_dwordx2 v[66:67], v[50:51], off offset:48
	v_lshlrev_b32_e32 v50, 16, v98
	v_mul_f32_e32 v51, 0xbfb8aa3b, v50
	v_exp_f32_e32 v52, v51
	v_and_b32_e32 v51, 0xffff0000, v98
	v_mul_f32_e32 v53, 0xbfb8aa3b, v51
	v_exp_f32_e32 v53, v53
	v_and_b32_e32 v55, 0xffff0000, v99
	v_add_f32_e32 v52, 1.0, v52
	v_mul_f32_e32 v56, 0xbfb8aa3b, v54
	v_add_f32_e32 v53, 1.0, v53
	v_mul_f32_e32 v57, 0xbfb8aa3b, v55
	v_rcp_f32_e32 v52, v52
	v_rcp_f32_e32 v53, v53
	v_exp_f32_e32 v56, v56
	v_exp_f32_e32 v57, v57
	v_pk_mul_f32 v[50:51], v[52:53], v[50:51]
	v_add_f32_e32 v52, 1.0, v56
	v_add_f32_e32 v53, 1.0, v57
	v_rcp_f32_e32 v52, v52
	v_rcp_f32_e32 v53, v53
	v_pk_mul_f32 v[34:35], v[34:35], v[50:51]
	v_pk_mul_f32 v[50:51], v[52:53], v[54:55]
	s_nop 0
	v_pk_mul_f32 v[36:37], v[36:37], v[50:51]
	v_cvt_pk_bf16_f32 v34, v34, v35
	v_cvt_pk_bf16_f32 v35, v36, v37
	global_store_dwordx2 v[66:67], v[34:35], off offset:64
	s_waitcnt vmcnt(15)
	v_lshlrev_b32_e32 v34, 16, v88
	v_mul_f32_e32 v35, 0xbfb8aa3b, v34
	v_exp_f32_e32 v36, v35
	v_and_b32_e32 v35, 0xffff0000, v88
	v_mul_f32_e32 v37, 0xbfb8aa3b, v35
	v_exp_f32_e32 v37, v37
	v_lshlrev_b32_e32 v50, 16, v89
	v_and_b32_e32 v51, 0xffff0000, v89
	v_add_f32_e32 v36, 1.0, v36
	v_add_f32_e32 v37, 1.0, v37
	v_mul_f32_e32 v52, 0xbfb8aa3b, v50
	v_mul_f32_e32 v53, 0xbfb8aa3b, v51
	v_rcp_f32_e32 v36, v36
	v_rcp_f32_e32 v37, v37
	v_exp_f32_e32 v52, v52
	v_exp_f32_e32 v53, v53
	v_pk_mul_f32 v[34:35], v[36:37], v[34:35]
	v_add_f32_e32 v36, 1.0, v52
	v_add_f32_e32 v37, 1.0, v53
	v_rcp_f32_e32 v36, v36
	v_rcp_f32_e32 v37, v37
	v_pk_mul_f32 v[34:35], v[38:39], v[34:35]
	v_pk_mul_f32 v[38:39], v[40:41], v[0:1] op_sel_hi:[1,0]
	v_cvt_pk_bf16_f32 v34, v34, v35
	v_pk_mul_f32 v[36:37], v[36:37], v[50:51]
	s_waitcnt vmcnt(14)
	v_lshlrev_b32_e32 v40, 16, v87
	v_pk_mul_f32 v[36:37], v[38:39], v[36:37]
	v_and_b32_e32 v41, 0xffff0000, v87
	v_cvt_pk_bf16_f32 v35, v36, v37
	global_store_dwordx2 v[66:67], v[34:35], off offset:80
	v_lshlrev_b32_e32 v34, 16, v86
	v_mul_f32_e32 v35, 0xbfb8aa3b, v34
	v_exp_f32_e32 v36, v35
	v_and_b32_e32 v35, 0xffff0000, v86
	v_mul_f32_e32 v37, 0xbfb8aa3b, v35
	v_exp_f32_e32 v37, v37
	v_add_f32_e32 v36, 1.0, v36
	v_pk_mul_f32 v[38:39], v[42:43], v[0:1] op_sel_hi:[1,0]
	v_mul_f32_e32 v42, 0xbfb8aa3b, v40
	v_add_f32_e32 v37, 1.0, v37
	v_mul_f32_e32 v43, 0xbfb8aa3b, v41
	v_rcp_f32_e32 v36, v36
	v_rcp_f32_e32 v37, v37
	v_exp_f32_e32 v42, v42
	v_exp_f32_e32 v43, v43
	v_pk_mul_f32 v[34:35], v[36:37], v[34:35]
	v_add_f32_e32 v36, 1.0, v42
	v_add_f32_e32 v37, 1.0, v43
	v_rcp_f32_e32 v36, v36
	v_rcp_f32_e32 v37, v37
	v_pk_mul_f32 v[34:35], v[38:39], v[34:35]
	v_pk_mul_f32 v[38:39], v[44:45], v[0:1] op_sel_hi:[1,0]
	v_cvt_pk_bf16_f32 v34, v34, v35
	v_pk_mul_f32 v[36:37], v[36:37], v[40:41]
	s_waitcnt vmcnt(14)
	v_lshlrev_b32_e32 v40, 16, v85
	v_pk_mul_f32 v[36:37], v[38:39], v[36:37]
	v_and_b32_e32 v41, 0xffff0000, v85
	v_cvt_pk_bf16_f32 v35, v36, v37
	global_store_dwordx2 v[66:67], v[34:35], off offset:96
	v_lshlrev_b32_e32 v34, 16, v84
	v_mul_f32_e32 v35, 0xbfb8aa3b, v34
	v_exp_f32_e32 v36, v35
	v_and_b32_e32 v35, 0xffff0000, v84
	v_mul_f32_e32 v37, 0xbfb8aa3b, v35
	v_exp_f32_e32 v37, v37
	v_add_f32_e32 v36, 1.0, v36
	v_mul_f32_e32 v42, 0xbfb8aa3b, v40
	v_mul_f32_e32 v43, 0xbfb8aa3b, v41
	v_add_f32_e32 v37, 1.0, v37
	v_rcp_f32_e32 v36, v36
	v_rcp_f32_e32 v37, v37
	v_exp_f32_e32 v42, v42
	v_exp_f32_e32 v43, v43
	v_pk_mul_f32 v[38:39], v[46:47], v[0:1] op_sel_hi:[1,0]
	v_pk_mul_f32 v[34:35], v[36:37], v[34:35]
	v_add_f32_e32 v36, 1.0, v42
	v_add_f32_e32 v37, 1.0, v43
	v_rcp_f32_e32 v36, v36
	v_rcp_f32_e32 v37, v37
	v_pk_mul_f32 v[34:35], v[38:39], v[34:35]
	v_pk_mul_f32 v[38:39], v[48:49], v[0:1] op_sel_hi:[1,0]
	v_cvt_pk_bf16_f32 v34, v34, v35
	v_pk_mul_f32 v[36:37], v[36:37], v[40:41]
	s_nop 0
	v_pk_mul_f32 v[36:37], v[38:39], v[36:37]
	s_waitcnt vmcnt(14)
	v_lshlrev_b32_e32 v38, 16, v83
	v_cvt_pk_bf16_f32 v35, v36, v37
	global_store_dwordx2 v[66:67], v[34:35], off offset:112
	v_lshlrev_b32_e32 v34, 16, v82
	v_mul_f32_e32 v35, 0xbfb8aa3b, v34
	v_exp_f32_e32 v36, v35
	v_and_b32_e32 v35, 0xffff0000, v82
	v_mul_f32_e32 v37, 0xbfb8aa3b, v35
	v_exp_f32_e32 v37, v37
	v_and_b32_e32 v39, 0xffff0000, v83
	v_add_f32_e32 v36, 1.0, v36
	v_mul_f32_e32 v40, 0xbfb8aa3b, v38
	v_add_f32_e32 v37, 1.0, v37
	v_mul_f32_e32 v41, 0xbfb8aa3b, v39
	v_rcp_f32_e32 v36, v36
	v_rcp_f32_e32 v37, v37
	v_exp_f32_e32 v40, v40
	v_exp_f32_e32 v41, v41
	v_pk_mul_f32 v[34:35], v[36:37], v[34:35]
	v_add_f32_e32 v36, 1.0, v40
	v_add_f32_e32 v37, 1.0, v41
	v_rcp_f32_e32 v36, v36
	v_rcp_f32_e32 v37, v37
	v_pk_mul_f32 v[18:19], v[18:19], v[34:35]
	v_pk_mul_f32 v[34:35], v[36:37], v[38:39]
	s_nop 0
	v_pk_mul_f32 v[20:21], v[20:21], v[34:35]
	v_cvt_pk_bf16_f32 v18, v18, v19
	v_cvt_pk_bf16_f32 v19, v20, v21
	global_store_dwordx2 v[66:67], v[18:19], off offset:128
	s_waitcnt vmcnt(15)
; __device__ __forceinline__ unsigned pk2(float lo, float hi) { f32x2 v = {lo, hi}; bf16x2_t b = __builtin_convertvector(v, bf16x2_t); return __builtin_bit_cast(unsigned, b); }
; __device__ __forceinline__ float silu_f(float z) { return z * __builtin_amdgcn_rcpf(1.0f + __expf(-z)); }
; template <int MODE>
; __device__ __forceinline__ void attn_unit(LAS unsigned char* lds, const bf16_t* __restrict__ qkvz, bf16_t* __restrict__ A2, const int b, const int hd, const int qb, const AttnX& X, const int tid) {
;     ...
; #pragma unroll
;         for (int d = 0; d < NDT; ++d)
; #pragma unroll
;             for (int i4 = 0; i4 < 4; ++i4) { const int dd = 32 * d + 8 * i4 + 4 * hh_e; const u32x2 z2 = zz[d * 4 + i4];
;                 u32x2 w;
;                 w.x = pk2(O[d][4 * i4 + 0] * inv * silu_f(bflo(z2.x)), O[d][4 * i4 + 1] * inv * silu_f(bfhi(z2.x)));
;                 w.y = pk2(O[d][4 * i4 + 2] * inv * silu_f(bflo(z2.y)), O[d][4 * i4 + 3] * inv * silu_f(bfhi(z2.y)));
;                 *(u32x2*)(A2 + trow * DM + hd * C::DV + dd) = w; }
;     ...
;     __syncthreads();
	v_lshlrev_b32_e32 v18, 16, v80
	v_mul_f32_e32 v19, 0xbfb8aa3b, v18
	v_exp_f32_e32 v20, v19
	v_and_b32_e32 v19, 0xffff0000, v80
	v_mul_f32_e32 v21, 0xbfb8aa3b, v19
	v_exp_f32_e32 v21, v21
	v_lshlrev_b32_e32 v34, 16, v81
	v_and_b32_e32 v35, 0xffff0000, v81
	v_add_f32_e32 v20, 1.0, v20
	v_add_f32_e32 v21, 1.0, v21
	v_mul_f32_e32 v36, 0xbfb8aa3b, v34
	v_mul_f32_e32 v37, 0xbfb8aa3b, v35
	v_rcp_f32_e32 v20, v20
	v_rcp_f32_e32 v21, v21
	v_exp_f32_e32 v36, v36
	v_exp_f32_e32 v37, v37
	v_pk_mul_f32 v[18:19], v[20:21], v[18:19]
	v_add_f32_e32 v20, 1.0, v36
	v_add_f32_e32 v21, 1.0, v37
	v_rcp_f32_e32 v20, v20
	v_rcp_f32_e32 v21, v21
	v_pk_mul_f32 v[18:19], v[22:23], v[18:19]
	v_pk_mul_f32 v[22:23], v[24:25], v[0:1] op_sel_hi:[1,0]
	v_cvt_pk_bf16_f32 v18, v18, v19
	v_pk_mul_f32 v[20:21], v[20:21], v[34:35]
	s_waitcnt vmcnt(14)
	v_lshlrev_b32_e32 v24, 16, v79
	v_pk_mul_f32 v[20:21], v[22:23], v[20:21]
	v_and_b32_e32 v25, 0xffff0000, v79
	v_cvt_pk_bf16_f32 v19, v20, v21
	global_store_dwordx2 v[66:67], v[18:19], off offset:144
	v_lshlrev_b32_e32 v18, 16, v78
	v_mul_f32_e32 v19, 0xbfb8aa3b, v18
	v_exp_f32_e32 v20, v19
	v_and_b32_e32 v19, 0xffff0000, v78
	v_mul_f32_e32 v21, 0xbfb8aa3b, v19
	v_exp_f32_e32 v21, v21
	v_add_f32_e32 v20, 1.0, v20
	v_pk_mul_f32 v[22:23], v[26:27], v[0:1] op_sel_hi:[1,0]
	v_mul_f32_e32 v26, 0xbfb8aa3b, v24
	v_add_f32_e32 v21, 1.0, v21
	v_mul_f32_e32 v27, 0xbfb8aa3b, v25
	v_rcp_f32_e32 v20, v20
	v_rcp_f32_e32 v21, v21
	v_exp_f32_e32 v26, v26
	v_exp_f32_e32 v27, v27
	v_pk_mul_f32 v[18:19], v[20:21], v[18:19]
	v_add_f32_e32 v20, 1.0, v26
	v_add_f32_e32 v21, 1.0, v27
	v_rcp_f32_e32 v20, v20
	v_rcp_f32_e32 v21, v21
	v_pk_mul_f32 v[18:19], v[22:23], v[18:19]
	v_pk_mul_f32 v[22:23], v[28:29], v[0:1] op_sel_hi:[1,0]
	v_cvt_pk_bf16_f32 v18, v18, v19
	v_pk_mul_f32 v[20:21], v[20:21], v[24:25]
	s_waitcnt vmcnt(14)
	v_lshlrev_b32_e32 v24, 16, v77
	v_pk_mul_f32 v[20:21], v[22:23], v[20:21]
	v_and_b32_e32 v25, 0xffff0000, v77
	v_cvt_pk_bf16_f32 v19, v20, v21
	global_store_dwordx2 v[66:67], v[18:19], off offset:160
	v_lshlrev_b32_e32 v18, 16, v76
	v_mul_f32_e32 v19, 0xbfb8aa3b, v18
	v_exp_f32_e32 v20, v19
	v_and_b32_e32 v19, 0xffff0000, v76
	v_mul_f32_e32 v21, 0xbfb8aa3b, v19
	v_exp_f32_e32 v21, v21
	v_add_f32_e32 v20, 1.0, v20
	v_mul_f32_e32 v26, 0xbfb8aa3b, v24
	v_mul_f32_e32 v27, 0xbfb8aa3b, v25
	v_add_f32_e32 v21, 1.0, v21
	v_rcp_f32_e32 v20, v20
	v_rcp_f32_e32 v21, v21
	v_exp_f32_e32 v26, v26
	v_exp_f32_e32 v27, v27
	v_pk_mul_f32 v[22:23], v[30:31], v[0:1] op_sel_hi:[1,0]
	v_pk_mul_f32 v[18:19], v[20:21], v[18:19]
	v_add_f32_e32 v20, 1.0, v26
	v_add_f32_e32 v21, 1.0, v27
	v_rcp_f32_e32 v20, v20
	v_rcp_f32_e32 v21, v21
	v_pk_mul_f32 v[18:19], v[22:23], v[18:19]
	v_pk_mul_f32 v[22:23], v[32:33], v[0:1] op_sel_hi:[1,0]
	v_cvt_pk_bf16_f32 v18, v18, v19
	v_pk_mul_f32 v[20:21], v[20:21], v[24:25]
	s_nop 0
	v_pk_mul_f32 v[20:21], v[22:23], v[20:21]
	s_waitcnt vmcnt(14)
	v_lshlrev_b32_e32 v22, 16, v75
	v_cvt_pk_bf16_f32 v19, v20, v21
	global_store_dwordx2 v[66:67], v[18:19], off offset:176
	v_lshlrev_b32_e32 v18, 16, v74
	v_mul_f32_e32 v19, 0xbfb8aa3b, v18
	v_exp_f32_e32 v20, v19
	v_and_b32_e32 v19, 0xffff0000, v74
	v_mul_f32_e32 v21, 0xbfb8aa3b, v19
	v_exp_f32_e32 v21, v21
	v_and_b32_e32 v23, 0xffff0000, v75
	v_add_f32_e32 v20, 1.0, v20
	v_mul_f32_e32 v24, 0xbfb8aa3b, v22
	v_add_f32_e32 v21, 1.0, v21
	v_mul_f32_e32 v25, 0xbfb8aa3b, v23
	v_rcp_f32_e32 v20, v20
	v_rcp_f32_e32 v21, v21
	v_exp_f32_e32 v24, v24
	v_exp_f32_e32 v25, v25
	v_pk_mul_f32 v[18:19], v[20:21], v[18:19]
	v_add_f32_e32 v20, 1.0, v24
	v_add_f32_e32 v21, 1.0, v25
	v_rcp_f32_e32 v20, v20
	v_rcp_f32_e32 v21, v21
	v_pk_mul_f32 v[2:3], v[2:3], v[18:19]
	v_pk_mul_f32 v[18:19], v[20:21], v[22:23]
	s_nop 0
	v_pk_mul_f32 v[4:5], v[4:5], v[18:19]
	v_cvt_pk_bf16_f32 v2, v2, v3
	v_cvt_pk_bf16_f32 v3, v4, v5
	global_store_dwordx2 v[66:67], v[2:3], off offset:192
	s_waitcnt vmcnt(15)
	v_lshlrev_b32_e32 v2, 16, v72
	v_mul_f32_e32 v3, 0xbfb8aa3b, v2
	v_exp_f32_e32 v4, v3
	v_and_b32_e32 v3, 0xffff0000, v72
	v_mul_f32_e32 v5, 0xbfb8aa3b, v3
	v_exp_f32_e32 v5, v5
	v_lshlrev_b32_e32 v18, 16, v73
	v_and_b32_e32 v19, 0xffff0000, v73
	v_add_f32_e32 v4, 1.0, v4
	v_add_f32_e32 v5, 1.0, v5
	v_mul_f32_e32 v20, 0xbfb8aa3b, v18
	v_mul_f32_e32 v21, 0xbfb8aa3b, v19
	v_rcp_f32_e32 v4, v4
	v_rcp_f32_e32 v5, v5
	v_exp_f32_e32 v20, v20
	v_exp_f32_e32 v21, v21
	v_pk_mul_f32 v[2:3], v[4:5], v[2:3]
	v_add_f32_e32 v4, 1.0, v20
	v_add_f32_e32 v5, 1.0, v21
	v_rcp_f32_e32 v4, v4
	v_rcp_f32_e32 v5, v5
	v_pk_mul_f32 v[2:3], v[6:7], v[2:3]
	v_pk_mul_f32 v[6:7], v[8:9], v[0:1] op_sel_hi:[1,0]
	v_cvt_pk_bf16_f32 v2, v2, v3
	v_pk_mul_f32 v[4:5], v[4:5], v[18:19]
	s_waitcnt vmcnt(14)
	v_lshlrev_b32_e32 v8, 16, v71
	v_pk_mul_f32 v[4:5], v[6:7], v[4:5]
	v_and_b32_e32 v9, 0xffff0000, v71
	v_cvt_pk_bf16_f32 v3, v4, v5
	global_store_dwordx2 v[66:67], v[2:3], off offset:208
	v_lshlrev_b32_e32 v2, 16, v70
	v_mul_f32_e32 v3, 0xbfb8aa3b, v2
	v_exp_f32_e32 v4, v3
	v_and_b32_e32 v3, 0xffff0000, v70
	v_mul_f32_e32 v5, 0xbfb8aa3b, v3
	v_exp_f32_e32 v5, v5
	v_add_f32_e32 v4, 1.0, v4
	v_pk_mul_f32 v[6:7], v[10:11], v[0:1] op_sel_hi:[1,0]
	v_mul_f32_e32 v10, 0xbfb8aa3b, v8
	v_add_f32_e32 v5, 1.0, v5
	v_mul_f32_e32 v11, 0xbfb8aa3b, v9
	v_rcp_f32_e32 v4, v4
	v_rcp_f32_e32 v5, v5
	v_exp_f32_e32 v10, v10
	v_exp_f32_e32 v11, v11
	v_pk_mul_f32 v[2:3], v[4:5], v[2:3]
	v_add_f32_e32 v4, 1.0, v10
	v_add_f32_e32 v5, 1.0, v11
	v_rcp_f32_e32 v4, v4
	v_rcp_f32_e32 v5, v5
	v_pk_mul_f32 v[2:3], v[6:7], v[2:3]
	v_pk_mul_f32 v[6:7], v[12:13], v[0:1] op_sel_hi:[1,0]
	v_cvt_pk_bf16_f32 v2, v2, v3
	v_pk_mul_f32 v[4:5], v[4:5], v[8:9]
	s_waitcnt vmcnt(14)
	v_lshlrev_b32_e32 v8, 16, v69
	v_pk_mul_f32 v[4:5], v[6:7], v[4:5]
	v_and_b32_e32 v9, 0xffff0000, v69
	v_cvt_pk_bf16_f32 v3, v4, v5
	global_store_dwordx2 v[66:67], v[2:3], off offset:224
	v_lshlrev_b32_e32 v2, 16, v68
	v_mul_f32_e32 v3, 0xbfb8aa3b, v2
	v_exp_f32_e32 v4, v3
	v_and_b32_e32 v3, 0xffff0000, v68
	v_mul_f32_e32 v5, 0xbfb8aa3b, v3
	v_exp_f32_e32 v5, v5
	v_add_f32_e32 v4, 1.0, v4
	v_mul_f32_e32 v10, 0xbfb8aa3b, v8
	v_mul_f32_e32 v11, 0xbfb8aa3b, v9
	v_add_f32_e32 v5, 1.0, v5
	v_rcp_f32_e32 v4, v4
	v_rcp_f32_e32 v5, v5
	v_exp_f32_e32 v10, v10
	v_exp_f32_e32 v11, v11
	v_pk_mul_f32 v[6:7], v[14:15], v[0:1] op_sel_hi:[1,0]
	v_pk_mul_f32 v[2:3], v[4:5], v[2:3]
	v_add_f32_e32 v4, 1.0, v10
	v_add_f32_e32 v5, 1.0, v11
	v_rcp_f32_e32 v4, v4
	v_rcp_f32_e32 v5, v5
	v_pk_mul_f32 v[2:3], v[6:7], v[2:3]
	v_pk_mul_f32 v[6:7], v[16:17], v[0:1] op_sel_hi:[1,0]
	v_cvt_pk_bf16_f32 v2, v2, v3
	v_pk_mul_f32 v[4:5], v[4:5], v[8:9]
	s_nop 0
	v_pk_mul_f32 v[4:5], v[6:7], v[4:5]
	s_nop 0
	v_cvt_pk_bf16_f32 v3, v4, v5
	global_store_dwordx2 v[66:67], v[2:3], off offset:240
	s_waitcnt lgkmcnt(0)
	s_barrier
; __device__ __forceinline__ void phase_attn_fox(const Params& p, LAS unsigned char* lds) {
;     ...
;     for (int u = bx; u < 2048; u += G) { const int j = u & 255, r = u >> 8, bh = j & 63, gg = j >> 6;
;         const int qb = 31 - ((r & 1) ? 4 * r + 3 - gg : 4 * r + gg);
;         attn_unit<2>(lds, QKVZ, A2, bh >> 4, bh & 15, qb, X, tid); }
	v_readlane_b32 s0, v254, 51
	v_readlane_b32 s1, v254, 52
	v_cmp_eq_u32_e32 vcc, 0, v212
	s_and_saveexec_b64 s[2:3], vcc
	s_cbranch_execz .Lfox_nofetch
	v_mov_b32_e32 v2, 0x93a0080
	v_mov_b32_e32 v3, 1
	s_nop 1
	global_atomic_add v2, v2, v3, s[0:1] sc0
	s_waitcnt vmcnt(0)
	v_mov_b32_e32 v3, 0x23ff8
	ds_write_b32 v3, v2
.Lfox_nofetch:
	s_or_b64 exec, exec, s[2:3]
	s_waitcnt lgkmcnt(0)
	s_barrier
	v_mov_b32_e32 v3, 0x23ff8
	ds_read_b32 v2, v3
	v_readlane_b32 s0, v254, 47
	s_waitcnt lgkmcnt(0)
	v_readfirstlane_b32 s87, v2
	s_nop 1
	s_add_i32 s87, s87, s0
	s_cmpk_lt_i32 s87, 0x800
	s_cbranch_scc0 .LBB0_1057
